# v13 plus out-projection epilogue loops unrolled with residual loads issued ahead (first loop before the pass barrier, second loop from inside the first loop's bodies)
# speedup vs baseline: 1.0343x; 1.0040x over previous
.LBB0_405:
	s_or_b64 exec, exec, s[14:15]
	v_lshl_add_u32 v138, s31, 7, v173
	v_ashrrev_i32_e32 v139, 31, v138
	v_lshlrev_b64 v[134:135], 10, v[138:139]
	v_lshl_add_u64 v[136:137], v[130:131], 0, v[134:135]
	v_readlane_b32 s36, v254, 6
	v_lshlrev_b64 v[140:141], 5, v[138:139]
	v_lshlrev_b64 v[176:177], 2, v[136:137]
	v_readlane_b32 s37, v254, 7
	s_xor_b64 s[12:13], s[12:13], -1
	v_lshl_add_u64 v[142:143], s[8:9], 0, v[140:141]
	v_lshl_add_u64 v[134:135], s[36:37], 0, v[176:177]
	v_lshl_add_u64 v[144:145], v[136:137], 1, s[0:1]
	v_lshl_add_u64 v[136:137], s[70:71], 0, v[176:177]
	s_mov_b64 s[14:15], 0
	v_mov_b32_e32 v128, v174
	s_mov_b64 s[14:15], 0
	v_lshl_add_u64 v[250:251], v[134:135], 0, s[14:15]
	global_load_dwordx4 v[202:205], v[250:251], off
	global_load_dwordx4 v[218:221], v[250:251], off offset:16
	s_add_u32 s14, s14, 0x20000
	s_addc_u32 s15, s15, 0
	v_lshl_add_u64 v[250:251], v[134:135], 0, s[14:15]
	global_load_dwordx4 v[206:209], v[250:251], off
	global_load_dwordx4 v[222:225], v[250:251], off offset:16
	s_add_u32 s14, s14, 0x20000
	s_addc_u32 s15, s15, 0
	v_lshl_add_u64 v[250:251], v[134:135], 0, s[14:15]
	global_load_dwordx4 v[210:213], v[250:251], off
	global_load_dwordx4 v[226:229], v[250:251], off offset:16
	s_add_u32 s14, s14, 0x20000
	s_addc_u32 s15, s15, 0
	v_lshl_add_u64 v[250:251], v[134:135], 0, s[14:15]
	global_load_dwordx4 v[214:217], v[250:251], off
	global_load_dwordx4 v[246:249], v[250:251], off offset:16
	s_add_u32 s14, s14, 0x20000
	s_addc_u32 s15, s15, 0
	s_mov_b64 s[14:15], 0
	s_waitcnt lgkmcnt(0)
	s_barrier
	v_readlane_b32 s38, v254, 8
	v_readlane_b32 s39, v254, 9
	v_readlane_b32 s40, v254, 10
	v_readlane_b32 s41, v254, 11
	v_readlane_b32 s42, v254, 12
	v_readlane_b32 s43, v254, 13
	v_readlane_b32 s44, v254, 14
	v_readlane_b32 s45, v254, 15
	v_readlane_b32 s46, v254, 16
	v_readlane_b32 s47, v254, 17
	v_readlane_b32 s48, v254, 18
	v_readlane_b32 s49, v254, 19
	v_readlane_b32 s50, v254, 20
	v_readlane_b32 s51, v254, 21
	s_branch .LBB0_407
.LBB0_407:
	v_lshl_add_u64 v[176:177], v[134:135], 0, s[14:15]
	ds_read_b128 v[194:197], v128
	ds_read_b128 v[198:201], v128 offset:16
	v_lshl_add_u64 v[176:177], v[136:137], 0, s[14:15]
	s_waitcnt vmcnt(7) lgkmcnt(1)
	v_pk_add_f32 v[186:187], v[194:195], v[202:203]
	v_pk_add_f32 v[188:189], v[196:197], v[204:205]
	s_waitcnt vmcnt(6) lgkmcnt(0)
	v_pk_add_f32 v[190:191], v[198:199], v[218:219]
	v_pk_add_f32 v[192:193], v[200:201], v[220:221]
	v_lshl_add_u64 v[250:251], v[134:135], 0, s[14:15]
	global_load_dwordx4 v[202:205], v[250:251], off offset:512
	global_load_dwordx4 v[218:221], v[250:251], off offset:528
	global_store_dwordx4 v[176:177], v[186:189], off
	global_store_dwordx4 v[176:177], v[190:193], off offset:16
	v_pk_mul_f32 v[176:177], v[186:187], v[186:187]
	v_pk_mul_f32 v[180:181], v[188:189], v[188:189]
	v_add_f32_e32 v176, v176, v177
	v_add_f32_e32 v176, v176, v180
	v_cvt_pk_bf16_f32 v194, v186, v187
	v_pk_mul_f32 v[186:187], v[190:191], v[190:191]
	v_add_f32_e32 v176, v176, v181
	v_add_f32_e32 v176, v176, v186
	v_cvt_pk_bf16_f32 v195, v188, v189
	v_pk_mul_f32 v[188:189], v[192:193], v[192:193]
	v_add_f32_e32 v176, v176, v187
	v_add_f32_e32 v176, v176, v188
	v_add_f32_e32 v176, v176, v189
	v_cvt_pk_bf16_f32 v196, v190, v191
	v_cvt_pk_bf16_f32 v197, v192, v193
	v_add_f32_dpp v176, v176, v176 quad_perm:[1,0,3,2] row_mask:0xf bank_mask:0xf bound_ctrl:1
	global_store_dwordx4 v[144:145], v[194:197], off offset:-8
	s_nop 0
	v_add_f32_dpp v176, v176, v176 quad_perm:[2,3,0,1] row_mask:0xf bank_mask:0xf bound_ctrl:1
	s_nop 1
	v_add_f32_dpp v176, v176, v176 row_ror:4 row_mask:0xf bank_mask:0xf bound_ctrl:1
	s_nop 1
	v_mov_b32_dpp v177, v176 row_ror:8 row_mask:0xf bank_mask:0xf bound_ctrl:1
	s_and_saveexec_b64 s[16:17], s[4:5]
	s_cbranch_execz .Lop_o0a_0
	v_add_f32_e32 v176, v176, v177
	global_store_dword v[142:143], v176, off
.Lop_o0a_0:
	s_or_b64 exec, exec, s[16:17]
	s_add_u32 s14, s14, 0x20000
	s_addc_u32 s15, s15, 0
	v_lshl_add_u64 v[142:143], v[142:143], 0, s[2:3]
	v_add_u32_e32 v128, 0x8200, v128
	s_cmp_lg_u32 s14, 0x80000
	v_lshl_add_u64 v[144:145], v[144:145], 0, s[6:7]
	v_lshl_add_u64 v[176:177], v[134:135], 0, s[14:15]
	ds_read_b128 v[194:197], v128
	ds_read_b128 v[198:201], v128 offset:16
	v_lshl_add_u64 v[176:177], v[136:137], 0, s[14:15]
	s_waitcnt vmcnt(11) lgkmcnt(1)
	v_pk_add_f32 v[186:187], v[194:195], v[206:207]
	v_pk_add_f32 v[188:189], v[196:197], v[208:209]
	s_waitcnt vmcnt(10) lgkmcnt(0)
	v_pk_add_f32 v[190:191], v[198:199], v[222:223]
	v_pk_add_f32 v[192:193], v[200:201], v[224:225]
	v_lshl_add_u64 v[250:251], v[134:135], 0, s[14:15]
	global_load_dwordx4 v[206:209], v[250:251], off offset:512
	global_load_dwordx4 v[222:225], v[250:251], off offset:528
	global_store_dwordx4 v[176:177], v[186:189], off
	global_store_dwordx4 v[176:177], v[190:193], off offset:16
	v_pk_mul_f32 v[176:177], v[186:187], v[186:187]
	v_pk_mul_f32 v[180:181], v[188:189], v[188:189]
	v_add_f32_e32 v176, v176, v177
	v_add_f32_e32 v176, v176, v180
	v_cvt_pk_bf16_f32 v194, v186, v187
	v_pk_mul_f32 v[186:187], v[190:191], v[190:191]
	v_add_f32_e32 v176, v176, v181
	v_add_f32_e32 v176, v176, v186
	v_cvt_pk_bf16_f32 v195, v188, v189
	v_pk_mul_f32 v[188:189], v[192:193], v[192:193]
	v_add_f32_e32 v176, v176, v187
	v_add_f32_e32 v176, v176, v188
	v_add_f32_e32 v176, v176, v189
	v_cvt_pk_bf16_f32 v196, v190, v191
	v_cvt_pk_bf16_f32 v197, v192, v193
	v_add_f32_dpp v176, v176, v176 quad_perm:[1,0,3,2] row_mask:0xf bank_mask:0xf bound_ctrl:1
	global_store_dwordx4 v[144:145], v[194:197], off offset:-8
	s_nop 0
	v_add_f32_dpp v176, v176, v176 quad_perm:[2,3,0,1] row_mask:0xf bank_mask:0xf bound_ctrl:1
	s_nop 1
	v_add_f32_dpp v176, v176, v176 row_ror:4 row_mask:0xf bank_mask:0xf bound_ctrl:1
	s_nop 1
	v_mov_b32_dpp v177, v176 row_ror:8 row_mask:0xf bank_mask:0xf bound_ctrl:1
	s_and_saveexec_b64 s[16:17], s[4:5]
	s_cbranch_execz .Lop_o0a_1
	v_add_f32_e32 v176, v176, v177
	global_store_dword v[142:143], v176, off
.Lop_o0a_1:
	s_or_b64 exec, exec, s[16:17]
	s_add_u32 s14, s14, 0x20000
	s_addc_u32 s15, s15, 0
	v_lshl_add_u64 v[142:143], v[142:143], 0, s[2:3]
	v_add_u32_e32 v128, 0x8200, v128
	s_cmp_lg_u32 s14, 0x80000
	v_lshl_add_u64 v[144:145], v[144:145], 0, s[6:7]
	v_lshl_add_u64 v[176:177], v[134:135], 0, s[14:15]
	ds_read_b128 v[194:197], v128
	ds_read_b128 v[198:201], v128 offset:16
	v_lshl_add_u64 v[176:177], v[136:137], 0, s[14:15]
	s_waitcnt vmcnt(15) lgkmcnt(1)
	v_pk_add_f32 v[186:187], v[194:195], v[210:211]
	v_pk_add_f32 v[188:189], v[196:197], v[212:213]
	s_waitcnt vmcnt(14) lgkmcnt(0)
	v_pk_add_f32 v[190:191], v[198:199], v[226:227]
	v_pk_add_f32 v[192:193], v[200:201], v[228:229]
	v_lshl_add_u64 v[250:251], v[134:135], 0, s[14:15]
	global_load_dwordx4 v[210:213], v[250:251], off offset:512
	global_load_dwordx4 v[226:229], v[250:251], off offset:528
	global_store_dwordx4 v[176:177], v[186:189], off
	global_store_dwordx4 v[176:177], v[190:193], off offset:16
	v_pk_mul_f32 v[176:177], v[186:187], v[186:187]
	v_pk_mul_f32 v[180:181], v[188:189], v[188:189]
	v_add_f32_e32 v176, v176, v177
	v_add_f32_e32 v176, v176, v180
	v_cvt_pk_bf16_f32 v194, v186, v187
	v_pk_mul_f32 v[186:187], v[190:191], v[190:191]
	v_add_f32_e32 v176, v176, v181
	v_add_f32_e32 v176, v176, v186
	v_cvt_pk_bf16_f32 v195, v188, v189
	v_pk_mul_f32 v[188:189], v[192:193], v[192:193]
	v_add_f32_e32 v176, v176, v187
	v_add_f32_e32 v176, v176, v188
	v_add_f32_e32 v176, v176, v189
	v_cvt_pk_bf16_f32 v196, v190, v191
	v_cvt_pk_bf16_f32 v197, v192, v193
	v_add_f32_dpp v176, v176, v176 quad_perm:[1,0,3,2] row_mask:0xf bank_mask:0xf bound_ctrl:1
	global_store_dwordx4 v[144:145], v[194:197], off offset:-8
	s_nop 0
	v_add_f32_dpp v176, v176, v176 quad_perm:[2,3,0,1] row_mask:0xf bank_mask:0xf bound_ctrl:1
	s_nop 1
	v_add_f32_dpp v176, v176, v176 row_ror:4 row_mask:0xf bank_mask:0xf bound_ctrl:1
	s_nop 1
	v_mov_b32_dpp v177, v176 row_ror:8 row_mask:0xf bank_mask:0xf bound_ctrl:1
	s_and_saveexec_b64 s[16:17], s[4:5]
	s_cbranch_execz .Lop_o0a_2
	v_add_f32_e32 v176, v176, v177
	global_store_dword v[142:143], v176, off
.Lop_o0a_2:
	s_or_b64 exec, exec, s[16:17]
	s_add_u32 s14, s14, 0x20000
	s_addc_u32 s15, s15, 0
	v_lshl_add_u64 v[142:143], v[142:143], 0, s[2:3]
	v_add_u32_e32 v128, 0x8200, v128
	s_cmp_lg_u32 s14, 0x80000
	v_lshl_add_u64 v[144:145], v[144:145], 0, s[6:7]
	v_lshl_add_u64 v[176:177], v[134:135], 0, s[14:15]
	ds_read_b128 v[194:197], v128
	ds_read_b128 v[198:201], v128 offset:16
	v_lshl_add_u64 v[176:177], v[136:137], 0, s[14:15]
	s_waitcnt vmcnt(19) lgkmcnt(1)
	v_pk_add_f32 v[186:187], v[194:195], v[214:215]
	v_pk_add_f32 v[188:189], v[196:197], v[216:217]
	s_waitcnt vmcnt(18) lgkmcnt(0)
	v_pk_add_f32 v[190:191], v[198:199], v[246:247]
	v_pk_add_f32 v[192:193], v[200:201], v[248:249]
	v_lshl_add_u64 v[250:251], v[134:135], 0, s[14:15]
	global_load_dwordx4 v[214:217], v[250:251], off offset:512
	global_load_dwordx4 v[246:249], v[250:251], off offset:528
	global_store_dwordx4 v[176:177], v[186:189], off
	global_store_dwordx4 v[176:177], v[190:193], off offset:16
	v_pk_mul_f32 v[176:177], v[186:187], v[186:187]
	v_pk_mul_f32 v[180:181], v[188:189], v[188:189]
	v_add_f32_e32 v176, v176, v177
	v_add_f32_e32 v176, v176, v180
	v_cvt_pk_bf16_f32 v194, v186, v187
	v_pk_mul_f32 v[186:187], v[190:191], v[190:191]
	v_add_f32_e32 v176, v176, v181
	v_add_f32_e32 v176, v176, v186
	v_cvt_pk_bf16_f32 v195, v188, v189
	v_pk_mul_f32 v[188:189], v[192:193], v[192:193]
	v_add_f32_e32 v176, v176, v187
	v_add_f32_e32 v176, v176, v188
	v_add_f32_e32 v176, v176, v189
	v_cvt_pk_bf16_f32 v196, v190, v191
	v_cvt_pk_bf16_f32 v197, v192, v193
	v_add_f32_dpp v176, v176, v176 quad_perm:[1,0,3,2] row_mask:0xf bank_mask:0xf bound_ctrl:1
	global_store_dwordx4 v[144:145], v[194:197], off offset:-8
	s_nop 0
	v_add_f32_dpp v176, v176, v176 quad_perm:[2,3,0,1] row_mask:0xf bank_mask:0xf bound_ctrl:1
	s_nop 1
	v_add_f32_dpp v176, v176, v176 row_ror:4 row_mask:0xf bank_mask:0xf bound_ctrl:1
	s_nop 1
	v_mov_b32_dpp v177, v176 row_ror:8 row_mask:0xf bank_mask:0xf bound_ctrl:1
	s_and_saveexec_b64 s[16:17], s[4:5]
	s_cbranch_execz .Lop_o0a_3
	v_add_f32_e32 v176, v176, v177
	global_store_dword v[142:143], v176, off
.Lop_o0a_3:
	s_or_b64 exec, exec, s[16:17]
	s_add_u32 s14, s14, 0x20000
	s_addc_u32 s15, s15, 0
	v_lshl_add_u64 v[142:143], v[142:143], 0, s[2:3]
	v_add_u32_e32 v128, 0x8200, v128
	s_cmp_lg_u32 s14, 0x80000
	v_lshl_add_u64 v[144:145], v[144:145], 0, s[6:7]
.LBB0_409:
	v_lshlrev_b64 v[138:139], 11, v[138:139]
	v_lshl_add_u64 v[140:141], s[10:11], 0, v[140:141]
	v_lshl_add_u64 v[138:139], v[132:133], 0, v[138:139]
	s_mov_b64 s[14:15], 0
	v_mov_b32_e32 v128, v175
	s_branch .LBB0_411
.LBB0_411:
	v_lshl_add_u64 v[176:177], v[134:135], 0, s[14:15]
	ds_read_b128 v[190:193], v128
	ds_read_b128 v[194:197], v128 offset:16
	v_lshl_add_u64 v[176:177], v[136:137], 0, s[14:15]
	s_waitcnt vmcnt(23) lgkmcnt(1)
	v_pk_add_f32 v[142:143], v[190:191], v[202:203]
	v_pk_add_f32 v[144:145], v[192:193], v[204:205]
	s_waitcnt vmcnt(22) lgkmcnt(0)
	v_pk_add_f32 v[186:187], v[194:195], v[218:219]
	v_pk_add_f32 v[188:189], v[196:197], v[220:221]
	global_store_dwordx4 v[176:177], v[142:145], off offset:512
	global_store_dwordx4 v[176:177], v[186:189], off offset:528
	v_cvt_pk_bf16_f32 v190, v142, v143
	v_pk_mul_f32 v[142:143], v[142:143], v[142:143]
	v_cvt_pk_bf16_f32 v191, v144, v145
	v_pk_mul_f32 v[144:145], v[144:145], v[144:145]
	v_add_f32_e32 v142, v142, v143
	v_add_f32_e32 v142, v142, v144
	v_pk_mul_f32 v[176:177], v[186:187], v[186:187]
	v_add_f32_e32 v142, v142, v145
	v_add_f32_e32 v142, v142, v176
	v_pk_mul_f32 v[180:181], v[188:189], v[188:189]
	v_add_f32_e32 v142, v142, v177
	v_add_f32_e32 v142, v142, v180
	v_add_f32_e32 v142, v142, v181
	v_cvt_pk_bf16_f32 v192, v186, v187
	v_cvt_pk_bf16_f32 v193, v188, v189
	v_add_f32_dpp v142, v142, v142 quad_perm:[1,0,3,2] row_mask:0xf bank_mask:0xf bound_ctrl:1
	global_store_dwordx4 v[138:139], v[190:193], off offset:-8
	s_nop 0
	v_add_f32_dpp v142, v142, v142 quad_perm:[2,3,0,1] row_mask:0xf bank_mask:0xf bound_ctrl:1
	s_nop 1
	v_add_f32_dpp v142, v142, v142 row_ror:4 row_mask:0xf bank_mask:0xf bound_ctrl:1
	s_nop 1
	v_mov_b32_dpp v143, v142 row_ror:8 row_mask:0xf bank_mask:0xf bound_ctrl:1
	s_and_saveexec_b64 s[16:17], s[4:5]
	s_cbranch_execz .Lop_o0b_0
	v_add_f32_e32 v142, v142, v143
	global_store_dword v[140:141], v142, off
.Lop_o0b_0:
	s_or_b64 exec, exec, s[16:17]
	s_add_u32 s14, s14, 0x20000
	s_addc_u32 s15, s15, 0
	v_lshl_add_u64 v[140:141], v[140:141], 0, s[2:3]
	v_add_u32_e32 v128, 0x8200, v128
	s_cmp_lg_u32 s14, 0x80000
	v_lshl_add_u64 v[138:139], v[138:139], 0, s[6:7]
	v_lshl_add_u64 v[176:177], v[134:135], 0, s[14:15]
	ds_read_b128 v[190:193], v128
	ds_read_b128 v[194:197], v128 offset:16
	v_lshl_add_u64 v[176:177], v[136:137], 0, s[14:15]
	s_waitcnt vmcnt(21) lgkmcnt(1)
	v_pk_add_f32 v[142:143], v[190:191], v[206:207]
	v_pk_add_f32 v[144:145], v[192:193], v[208:209]
	s_waitcnt vmcnt(20) lgkmcnt(0)
	v_pk_add_f32 v[186:187], v[194:195], v[222:223]
	v_pk_add_f32 v[188:189], v[196:197], v[224:225]
	global_store_dwordx4 v[176:177], v[142:145], off offset:512
	global_store_dwordx4 v[176:177], v[186:189], off offset:528
	v_cvt_pk_bf16_f32 v190, v142, v143
	v_pk_mul_f32 v[142:143], v[142:143], v[142:143]
	v_cvt_pk_bf16_f32 v191, v144, v145
	v_pk_mul_f32 v[144:145], v[144:145], v[144:145]
	v_add_f32_e32 v142, v142, v143
	v_add_f32_e32 v142, v142, v144
	v_pk_mul_f32 v[176:177], v[186:187], v[186:187]
	v_add_f32_e32 v142, v142, v145
	v_add_f32_e32 v142, v142, v176
	v_pk_mul_f32 v[180:181], v[188:189], v[188:189]
	v_add_f32_e32 v142, v142, v177
	v_add_f32_e32 v142, v142, v180
	v_add_f32_e32 v142, v142, v181
	v_cvt_pk_bf16_f32 v192, v186, v187
	v_cvt_pk_bf16_f32 v193, v188, v189
	v_add_f32_dpp v142, v142, v142 quad_perm:[1,0,3,2] row_mask:0xf bank_mask:0xf bound_ctrl:1
	global_store_dwordx4 v[138:139], v[190:193], off offset:-8
	s_nop 0
	v_add_f32_dpp v142, v142, v142 quad_perm:[2,3,0,1] row_mask:0xf bank_mask:0xf bound_ctrl:1
	s_nop 1
	v_add_f32_dpp v142, v142, v142 row_ror:4 row_mask:0xf bank_mask:0xf bound_ctrl:1
	s_nop 1
	v_mov_b32_dpp v143, v142 row_ror:8 row_mask:0xf bank_mask:0xf bound_ctrl:1
	s_and_saveexec_b64 s[16:17], s[4:5]
	s_cbranch_execz .Lop_o0b_1
	v_add_f32_e32 v142, v142, v143
	global_store_dword v[140:141], v142, off
.Lop_o0b_1:
	s_or_b64 exec, exec, s[16:17]
	s_add_u32 s14, s14, 0x20000
	s_addc_u32 s15, s15, 0
	v_lshl_add_u64 v[140:141], v[140:141], 0, s[2:3]
	v_add_u32_e32 v128, 0x8200, v128
	s_cmp_lg_u32 s14, 0x80000
	v_lshl_add_u64 v[138:139], v[138:139], 0, s[6:7]
	v_lshl_add_u64 v[176:177], v[134:135], 0, s[14:15]
	ds_read_b128 v[190:193], v128
	ds_read_b128 v[194:197], v128 offset:16
	v_lshl_add_u64 v[176:177], v[136:137], 0, s[14:15]
	s_waitcnt vmcnt(19) lgkmcnt(1)
	v_pk_add_f32 v[142:143], v[190:191], v[210:211]
	v_pk_add_f32 v[144:145], v[192:193], v[212:213]
	s_waitcnt vmcnt(18) lgkmcnt(0)
	v_pk_add_f32 v[186:187], v[194:195], v[226:227]
	v_pk_add_f32 v[188:189], v[196:197], v[228:229]
	global_store_dwordx4 v[176:177], v[142:145], off offset:512
	global_store_dwordx4 v[176:177], v[186:189], off offset:528
	v_cvt_pk_bf16_f32 v190, v142, v143
	v_pk_mul_f32 v[142:143], v[142:143], v[142:143]
	v_cvt_pk_bf16_f32 v191, v144, v145
	v_pk_mul_f32 v[144:145], v[144:145], v[144:145]
	v_add_f32_e32 v142, v142, v143
	v_add_f32_e32 v142, v142, v144
	v_pk_mul_f32 v[176:177], v[186:187], v[186:187]
	v_add_f32_e32 v142, v142, v145
	v_add_f32_e32 v142, v142, v176
	v_pk_mul_f32 v[180:181], v[188:189], v[188:189]
	v_add_f32_e32 v142, v142, v177
	v_add_f32_e32 v142, v142, v180
	v_add_f32_e32 v142, v142, v181
	v_cvt_pk_bf16_f32 v192, v186, v187
	v_cvt_pk_bf16_f32 v193, v188, v189
	v_add_f32_dpp v142, v142, v142 quad_perm:[1,0,3,2] row_mask:0xf bank_mask:0xf bound_ctrl:1
	global_store_dwordx4 v[138:139], v[190:193], off offset:-8
	s_nop 0
	v_add_f32_dpp v142, v142, v142 quad_perm:[2,3,0,1] row_mask:0xf bank_mask:0xf bound_ctrl:1
	s_nop 1
	v_add_f32_dpp v142, v142, v142 row_ror:4 row_mask:0xf bank_mask:0xf bound_ctrl:1
	s_nop 1
	v_mov_b32_dpp v143, v142 row_ror:8 row_mask:0xf bank_mask:0xf bound_ctrl:1
	s_and_saveexec_b64 s[16:17], s[4:5]
	s_cbranch_execz .Lop_o0b_2
	v_add_f32_e32 v142, v142, v143
	global_store_dword v[140:141], v142, off
.Lop_o0b_2:
	s_or_b64 exec, exec, s[16:17]
	s_add_u32 s14, s14, 0x20000
	s_addc_u32 s15, s15, 0
	v_lshl_add_u64 v[140:141], v[140:141], 0, s[2:3]
	v_add_u32_e32 v128, 0x8200, v128
	s_cmp_lg_u32 s14, 0x80000
	v_lshl_add_u64 v[138:139], v[138:139], 0, s[6:7]
	v_lshl_add_u64 v[176:177], v[134:135], 0, s[14:15]
	ds_read_b128 v[190:193], v128
	ds_read_b128 v[194:197], v128 offset:16
	v_lshl_add_u64 v[176:177], v[136:137], 0, s[14:15]
	s_waitcnt vmcnt(17) lgkmcnt(1)
	v_pk_add_f32 v[142:143], v[190:191], v[214:215]
	v_pk_add_f32 v[144:145], v[192:193], v[216:217]
	s_waitcnt vmcnt(16) lgkmcnt(0)
	v_pk_add_f32 v[186:187], v[194:195], v[246:247]
	v_pk_add_f32 v[188:189], v[196:197], v[248:249]
	global_store_dwordx4 v[176:177], v[142:145], off offset:512
	global_store_dwordx4 v[176:177], v[186:189], off offset:528
	v_cvt_pk_bf16_f32 v190, v142, v143
	v_pk_mul_f32 v[142:143], v[142:143], v[142:143]
	v_cvt_pk_bf16_f32 v191, v144, v145
	v_pk_mul_f32 v[144:145], v[144:145], v[144:145]
	v_add_f32_e32 v142, v142, v143
	v_add_f32_e32 v142, v142, v144
	v_pk_mul_f32 v[176:177], v[186:187], v[186:187]
	v_add_f32_e32 v142, v142, v145
	v_add_f32_e32 v142, v142, v176
	v_pk_mul_f32 v[180:181], v[188:189], v[188:189]
	v_add_f32_e32 v142, v142, v177
	v_add_f32_e32 v142, v142, v180
	v_add_f32_e32 v142, v142, v181
	v_cvt_pk_bf16_f32 v192, v186, v187
	v_cvt_pk_bf16_f32 v193, v188, v189
	v_add_f32_dpp v142, v142, v142 quad_perm:[1,0,3,2] row_mask:0xf bank_mask:0xf bound_ctrl:1
	global_store_dwordx4 v[138:139], v[190:193], off offset:-8
	s_nop 0
	v_add_f32_dpp v142, v142, v142 quad_perm:[2,3,0,1] row_mask:0xf bank_mask:0xf bound_ctrl:1
	s_nop 1
	v_add_f32_dpp v142, v142, v142 row_ror:4 row_mask:0xf bank_mask:0xf bound_ctrl:1
	s_nop 1
	v_mov_b32_dpp v143, v142 row_ror:8 row_mask:0xf bank_mask:0xf bound_ctrl:1
	s_and_saveexec_b64 s[16:17], s[4:5]
	s_cbranch_execz .Lop_o0b_3
	v_add_f32_e32 v142, v142, v143
	global_store_dword v[140:141], v142, off
.Lop_o0b_3:
	s_or_b64 exec, exec, s[16:17]
	s_add_u32 s14, s14, 0x20000
	s_addc_u32 s15, s15, 0
	v_lshl_add_u64 v[140:141], v[140:141], 0, s[2:3]
	v_add_u32_e32 v128, 0x8200, v128
	s_cmp_lg_u32 s14, 0x80000
	v_lshl_add_u64 v[138:139], v[138:139], 0, s[6:7]
	s_branch .LBB0_402

.LBB0_990:
	s_or_b64 exec, exec, s[14:15]
	v_lshl_add_u32 v136, s31, 7, v171
	v_ashrrev_i32_e32 v137, 31, v136
	v_lshlrev_b64 v[134:135], 10, v[136:137]
	v_lshlrev_b64 v[138:139], 5, v[136:137]
	v_lshl_add_u64 v[142:143], v[130:131], 0, v[134:135]
	s_xor_b64 s[12:13], s[12:13], -1
	v_lshl_add_u64 v[140:141], s[8:9], 0, v[138:139]
	v_lshl_add_u64 v[134:135], v[142:143], 2, s[70:71]
	v_lshl_add_u64 v[142:143], v[142:143], 1, s[2:3]
	s_mov_b64 s[14:15], 0
	v_mov_b32_e32 v128, v172
	s_mov_b64 s[14:15], 0
	v_lshl_add_u64 v[250:251], v[134:135], 0, s[14:15]
	global_load_dwordx4 v[202:205], v[250:251], off
	global_load_dwordx4 v[218:221], v[250:251], off offset:16
	s_add_u32 s14, s14, 0x20000
	s_addc_u32 s15, s15, 0
	v_lshl_add_u64 v[250:251], v[134:135], 0, s[14:15]
	global_load_dwordx4 v[206:209], v[250:251], off
	global_load_dwordx4 v[222:225], v[250:251], off offset:16
	s_add_u32 s14, s14, 0x20000
	s_addc_u32 s15, s15, 0
	v_lshl_add_u64 v[250:251], v[134:135], 0, s[14:15]
	global_load_dwordx4 v[210:213], v[250:251], off
	global_load_dwordx4 v[226:229], v[250:251], off offset:16
	s_add_u32 s14, s14, 0x20000
	s_addc_u32 s15, s15, 0
	v_lshl_add_u64 v[250:251], v[134:135], 0, s[14:15]
	global_load_dwordx4 v[214:217], v[250:251], off
	global_load_dwordx4 v[230:233], v[250:251], off offset:16
	s_add_u32 s14, s14, 0x20000
	s_addc_u32 s15, s15, 0
	s_mov_b64 s[14:15], 0
	s_waitcnt lgkmcnt(0)
	s_barrier
	s_branch .LBB0_992
.LBB0_992:
	v_lshl_add_u64 v[180:181], v[134:135], 0, s[14:15]
	ds_read_b128 v[186:189], v128
	ds_read_b128 v[190:193], v128 offset:16
	s_waitcnt vmcnt(7) lgkmcnt(1)
	v_pk_add_f32 v[174:175], v[186:187], v[202:203]
	v_pk_add_f32 v[176:177], v[188:189], v[204:205]
	s_waitcnt vmcnt(6) lgkmcnt(0)
	v_pk_add_f32 v[182:183], v[190:191], v[218:219]
	v_pk_add_f32 v[184:185], v[192:193], v[220:221]
	v_lshl_add_u64 v[250:251], v[134:135], 0, s[14:15]
	global_load_dwordx4 v[202:205], v[250:251], off offset:512
	global_load_dwordx4 v[218:221], v[250:251], off offset:528
	global_store_dwordx4 v[180:181], v[174:177], off
	global_store_dwordx4 v[180:181], v[182:185], off offset:16
	v_cvt_pk_bf16_f32 v186, v174, v175
	v_pk_mul_f32 v[174:175], v[174:175], v[174:175]
	v_cvt_pk_bf16_f32 v187, v176, v177
	v_pk_mul_f32 v[176:177], v[176:177], v[176:177]
	v_add_f32_e32 v174, v174, v175
	v_add_f32_e32 v174, v174, v176
	v_pk_mul_f32 v[180:181], v[182:183], v[182:183]
	v_add_f32_e32 v174, v174, v177
	v_add_f32_e32 v174, v174, v180
	v_cvt_pk_bf16_f32 v188, v182, v183
	v_pk_mul_f32 v[182:183], v[184:185], v[184:185]
	v_add_f32_e32 v174, v174, v181
	v_add_f32_e32 v174, v174, v182
	v_add_f32_e32 v174, v174, v183
	v_cvt_pk_bf16_f32 v189, v184, v185
	global_store_dwordx4 v[142:143], v[186:189], off offset:-8
	v_add_f32_dpp v174, v174, v174 quad_perm:[1,0,3,2] row_mask:0xf bank_mask:0xf bound_ctrl:1
	s_nop 1
	v_add_f32_dpp v174, v174, v174 quad_perm:[2,3,0,1] row_mask:0xf bank_mask:0xf bound_ctrl:1
	s_nop 1
	v_add_f32_dpp v174, v174, v174 row_ror:4 row_mask:0xf bank_mask:0xf bound_ctrl:1
	s_nop 1
	v_mov_b32_dpp v175, v174 row_ror:8 row_mask:0xf bank_mask:0xf bound_ctrl:1
	s_and_saveexec_b64 s[16:17], s[0:1]
	s_cbranch_execz .Lop_o1a_0
	v_add_f32_e32 v174, v174, v175
	global_store_dword v[140:141], v174, off
.Lop_o1a_0:
	s_or_b64 exec, exec, s[16:17]
	s_add_u32 s14, s14, 0x20000
	s_addc_u32 s15, s15, 0
	v_lshl_add_u64 v[140:141], v[140:141], 0, s[4:5]
	v_add_u32_e32 v128, 0x8200, v128
	s_cmp_lg_u32 s14, 0x80000
	v_lshl_add_u64 v[142:143], v[142:143], 0, s[6:7]
	v_lshl_add_u64 v[180:181], v[134:135], 0, s[14:15]
	ds_read_b128 v[186:189], v128
	ds_read_b128 v[190:193], v128 offset:16
	s_waitcnt vmcnt(11) lgkmcnt(1)
	v_pk_add_f32 v[174:175], v[186:187], v[206:207]
	v_pk_add_f32 v[176:177], v[188:189], v[208:209]
	s_waitcnt vmcnt(10) lgkmcnt(0)
	v_pk_add_f32 v[182:183], v[190:191], v[222:223]
	v_pk_add_f32 v[184:185], v[192:193], v[224:225]
	v_lshl_add_u64 v[250:251], v[134:135], 0, s[14:15]
	global_load_dwordx4 v[206:209], v[250:251], off offset:512
	global_load_dwordx4 v[222:225], v[250:251], off offset:528
	global_store_dwordx4 v[180:181], v[174:177], off
	global_store_dwordx4 v[180:181], v[182:185], off offset:16
	v_cvt_pk_bf16_f32 v186, v174, v175
	v_pk_mul_f32 v[174:175], v[174:175], v[174:175]
	v_cvt_pk_bf16_f32 v187, v176, v177
	v_pk_mul_f32 v[176:177], v[176:177], v[176:177]
	v_add_f32_e32 v174, v174, v175
	v_add_f32_e32 v174, v174, v176
	v_pk_mul_f32 v[180:181], v[182:183], v[182:183]
	v_add_f32_e32 v174, v174, v177
	v_add_f32_e32 v174, v174, v180
	v_cvt_pk_bf16_f32 v188, v182, v183
	v_pk_mul_f32 v[182:183], v[184:185], v[184:185]
	v_add_f32_e32 v174, v174, v181
	v_add_f32_e32 v174, v174, v182
	v_add_f32_e32 v174, v174, v183
	v_cvt_pk_bf16_f32 v189, v184, v185
	global_store_dwordx4 v[142:143], v[186:189], off offset:-8
	v_add_f32_dpp v174, v174, v174 quad_perm:[1,0,3,2] row_mask:0xf bank_mask:0xf bound_ctrl:1
	s_nop 1
	v_add_f32_dpp v174, v174, v174 quad_perm:[2,3,0,1] row_mask:0xf bank_mask:0xf bound_ctrl:1
	s_nop 1
	v_add_f32_dpp v174, v174, v174 row_ror:4 row_mask:0xf bank_mask:0xf bound_ctrl:1
	s_nop 1
	v_mov_b32_dpp v175, v174 row_ror:8 row_mask:0xf bank_mask:0xf bound_ctrl:1
	s_and_saveexec_b64 s[16:17], s[0:1]
	s_cbranch_execz .Lop_o1a_1
	v_add_f32_e32 v174, v174, v175
	global_store_dword v[140:141], v174, off
.Lop_o1a_1:
	s_or_b64 exec, exec, s[16:17]
	s_add_u32 s14, s14, 0x20000
	s_addc_u32 s15, s15, 0
	v_lshl_add_u64 v[140:141], v[140:141], 0, s[4:5]
	v_add_u32_e32 v128, 0x8200, v128
	s_cmp_lg_u32 s14, 0x80000
	v_lshl_add_u64 v[142:143], v[142:143], 0, s[6:7]
	v_lshl_add_u64 v[180:181], v[134:135], 0, s[14:15]
	ds_read_b128 v[186:189], v128
	ds_read_b128 v[190:193], v128 offset:16
	s_waitcnt vmcnt(15) lgkmcnt(1)
	v_pk_add_f32 v[174:175], v[186:187], v[210:211]
	v_pk_add_f32 v[176:177], v[188:189], v[212:213]
	s_waitcnt vmcnt(14) lgkmcnt(0)
	v_pk_add_f32 v[182:183], v[190:191], v[226:227]
	v_pk_add_f32 v[184:185], v[192:193], v[228:229]
	v_lshl_add_u64 v[250:251], v[134:135], 0, s[14:15]
	global_load_dwordx4 v[210:213], v[250:251], off offset:512
	global_load_dwordx4 v[226:229], v[250:251], off offset:528
	global_store_dwordx4 v[180:181], v[174:177], off
	global_store_dwordx4 v[180:181], v[182:185], off offset:16
	v_cvt_pk_bf16_f32 v186, v174, v175
	v_pk_mul_f32 v[174:175], v[174:175], v[174:175]
	v_cvt_pk_bf16_f32 v187, v176, v177
	v_pk_mul_f32 v[176:177], v[176:177], v[176:177]
	v_add_f32_e32 v174, v174, v175
	v_add_f32_e32 v174, v174, v176
	v_pk_mul_f32 v[180:181], v[182:183], v[182:183]
	v_add_f32_e32 v174, v174, v177
	v_add_f32_e32 v174, v174, v180
	v_cvt_pk_bf16_f32 v188, v182, v183
	v_pk_mul_f32 v[182:183], v[184:185], v[184:185]
	v_add_f32_e32 v174, v174, v181
	v_add_f32_e32 v174, v174, v182
	v_add_f32_e32 v174, v174, v183
	v_cvt_pk_bf16_f32 v189, v184, v185
	global_store_dwordx4 v[142:143], v[186:189], off offset:-8
	v_add_f32_dpp v174, v174, v174 quad_perm:[1,0,3,2] row_mask:0xf bank_mask:0xf bound_ctrl:1
	s_nop 1
	v_add_f32_dpp v174, v174, v174 quad_perm:[2,3,0,1] row_mask:0xf bank_mask:0xf bound_ctrl:1
	s_nop 1
	v_add_f32_dpp v174, v174, v174 row_ror:4 row_mask:0xf bank_mask:0xf bound_ctrl:1
	s_nop 1
	v_mov_b32_dpp v175, v174 row_ror:8 row_mask:0xf bank_mask:0xf bound_ctrl:1
	s_and_saveexec_b64 s[16:17], s[0:1]
	s_cbranch_execz .Lop_o1a_2
	v_add_f32_e32 v174, v174, v175
	global_store_dword v[140:141], v174, off
.Lop_o1a_2:
	s_or_b64 exec, exec, s[16:17]
	s_add_u32 s14, s14, 0x20000
	s_addc_u32 s15, s15, 0
	v_lshl_add_u64 v[140:141], v[140:141], 0, s[4:5]
	v_add_u32_e32 v128, 0x8200, v128
	s_cmp_lg_u32 s14, 0x80000
	v_lshl_add_u64 v[142:143], v[142:143], 0, s[6:7]
	v_lshl_add_u64 v[180:181], v[134:135], 0, s[14:15]
	ds_read_b128 v[186:189], v128
	ds_read_b128 v[190:193], v128 offset:16
	s_waitcnt vmcnt(19) lgkmcnt(1)
	v_pk_add_f32 v[174:175], v[186:187], v[214:215]
	v_pk_add_f32 v[176:177], v[188:189], v[216:217]
	s_waitcnt vmcnt(18) lgkmcnt(0)
	v_pk_add_f32 v[182:183], v[190:191], v[230:231]
	v_pk_add_f32 v[184:185], v[192:193], v[232:233]
	v_lshl_add_u64 v[250:251], v[134:135], 0, s[14:15]
	global_load_dwordx4 v[214:217], v[250:251], off offset:512
	global_load_dwordx4 v[230:233], v[250:251], off offset:528
	global_store_dwordx4 v[180:181], v[174:177], off
	global_store_dwordx4 v[180:181], v[182:185], off offset:16
	v_cvt_pk_bf16_f32 v186, v174, v175
	v_pk_mul_f32 v[174:175], v[174:175], v[174:175]
	v_cvt_pk_bf16_f32 v187, v176, v177
	v_pk_mul_f32 v[176:177], v[176:177], v[176:177]
	v_add_f32_e32 v174, v174, v175
	v_add_f32_e32 v174, v174, v176
	v_pk_mul_f32 v[180:181], v[182:183], v[182:183]
	v_add_f32_e32 v174, v174, v177
	v_add_f32_e32 v174, v174, v180
	v_cvt_pk_bf16_f32 v188, v182, v183
	v_pk_mul_f32 v[182:183], v[184:185], v[184:185]
	v_add_f32_e32 v174, v174, v181
	v_add_f32_e32 v174, v174, v182
	v_add_f32_e32 v174, v174, v183
	v_cvt_pk_bf16_f32 v189, v184, v185
	global_store_dwordx4 v[142:143], v[186:189], off offset:-8
	v_add_f32_dpp v174, v174, v174 quad_perm:[1,0,3,2] row_mask:0xf bank_mask:0xf bound_ctrl:1
	s_nop 1
	v_add_f32_dpp v174, v174, v174 quad_perm:[2,3,0,1] row_mask:0xf bank_mask:0xf bound_ctrl:1
	s_nop 1
	v_add_f32_dpp v174, v174, v174 row_ror:4 row_mask:0xf bank_mask:0xf bound_ctrl:1
	s_nop 1
	v_mov_b32_dpp v175, v174 row_ror:8 row_mask:0xf bank_mask:0xf bound_ctrl:1
	s_and_saveexec_b64 s[16:17], s[0:1]
	s_cbranch_execz .Lop_o1a_3
	v_add_f32_e32 v174, v174, v175
	global_store_dword v[140:141], v174, off
.Lop_o1a_3:
	s_or_b64 exec, exec, s[16:17]
	s_add_u32 s14, s14, 0x20000
	s_addc_u32 s15, s15, 0
	v_lshl_add_u64 v[140:141], v[140:141], 0, s[4:5]
	v_add_u32_e32 v128, 0x8200, v128
	s_cmp_lg_u32 s14, 0x80000
	v_lshl_add_u64 v[142:143], v[142:143], 0, s[6:7]
.LBB0_994:
	v_lshlrev_b64 v[136:137], 11, v[136:137]
	v_lshl_add_u64 v[138:139], s[10:11], 0, v[138:139]
	v_lshl_add_u64 v[136:137], v[132:133], 0, v[136:137]
	s_mov_b64 s[14:15], 0
	v_mov_b32_e32 v128, v173
	s_branch .LBB0_996
.LBB0_996:
	v_lshl_add_u64 v[180:181], v[134:135], 0, s[14:15]
	ds_read_b128 v[182:185], v128
	ds_read_b128 v[186:189], v128 offset:16
	s_waitcnt vmcnt(23) lgkmcnt(1)
	v_pk_add_f32 v[140:141], v[182:183], v[202:203]
	v_pk_add_f32 v[142:143], v[184:185], v[204:205]
	s_waitcnt vmcnt(22) lgkmcnt(0)
	v_pk_add_f32 v[174:175], v[186:187], v[218:219]
	v_pk_add_f32 v[176:177], v[188:189], v[220:221]
	global_store_dwordx4 v[180:181], v[140:143], off offset:512
	global_store_dwordx4 v[180:181], v[174:177], off offset:528
	v_cvt_pk_bf16_f32 v182, v140, v141
	v_pk_mul_f32 v[140:141], v[140:141], v[140:141]
	v_cvt_pk_bf16_f32 v183, v142, v143
	v_pk_mul_f32 v[142:143], v[142:143], v[142:143]
	v_add_f32_e32 v140, v140, v141
	v_add_f32_e32 v140, v140, v142
	v_cvt_pk_bf16_f32 v184, v174, v175
	v_pk_mul_f32 v[174:175], v[174:175], v[174:175]
	v_add_f32_e32 v140, v140, v143
	v_add_f32_e32 v140, v140, v174
	v_cvt_pk_bf16_f32 v185, v176, v177
	v_pk_mul_f32 v[176:177], v[176:177], v[176:177]
	v_add_f32_e32 v140, v140, v175
	v_add_f32_e32 v140, v140, v176
	v_add_f32_e32 v140, v140, v177
	global_store_dwordx4 v[136:137], v[182:185], off offset:-8
	s_nop 0
	v_add_f32_dpp v140, v140, v140 quad_perm:[1,0,3,2] row_mask:0xf bank_mask:0xf bound_ctrl:1
	s_nop 1
	v_add_f32_dpp v140, v140, v140 quad_perm:[2,3,0,1] row_mask:0xf bank_mask:0xf bound_ctrl:1
	s_nop 1
	v_add_f32_dpp v140, v140, v140 row_ror:4 row_mask:0xf bank_mask:0xf bound_ctrl:1
	s_nop 1
	v_mov_b32_dpp v141, v140 row_ror:8 row_mask:0xf bank_mask:0xf bound_ctrl:1
	s_and_saveexec_b64 s[16:17], s[0:1]
	s_cbranch_execz .Lop_o1b_0
	v_add_f32_e32 v140, v140, v141
	global_store_dword v[138:139], v140, off
.Lop_o1b_0:
	s_or_b64 exec, exec, s[16:17]
	s_add_u32 s14, s14, 0x20000
	s_addc_u32 s15, s15, 0
	v_lshl_add_u64 v[138:139], v[138:139], 0, s[4:5]
	v_add_u32_e32 v128, 0x8200, v128
	s_cmp_lg_u32 s14, 0x80000
	v_lshl_add_u64 v[136:137], v[136:137], 0, s[6:7]
	v_lshl_add_u64 v[180:181], v[134:135], 0, s[14:15]
	ds_read_b128 v[182:185], v128
	ds_read_b128 v[186:189], v128 offset:16
	s_waitcnt vmcnt(21) lgkmcnt(1)
	v_pk_add_f32 v[140:141], v[182:183], v[206:207]
	v_pk_add_f32 v[142:143], v[184:185], v[208:209]
	s_waitcnt vmcnt(20) lgkmcnt(0)
	v_pk_add_f32 v[174:175], v[186:187], v[222:223]
	v_pk_add_f32 v[176:177], v[188:189], v[224:225]
	global_store_dwordx4 v[180:181], v[140:143], off offset:512
	global_store_dwordx4 v[180:181], v[174:177], off offset:528
	v_cvt_pk_bf16_f32 v182, v140, v141
	v_pk_mul_f32 v[140:141], v[140:141], v[140:141]
	v_cvt_pk_bf16_f32 v183, v142, v143
	v_pk_mul_f32 v[142:143], v[142:143], v[142:143]
	v_add_f32_e32 v140, v140, v141
	v_add_f32_e32 v140, v140, v142
	v_cvt_pk_bf16_f32 v184, v174, v175
	v_pk_mul_f32 v[174:175], v[174:175], v[174:175]
	v_add_f32_e32 v140, v140, v143
	v_add_f32_e32 v140, v140, v174
	v_cvt_pk_bf16_f32 v185, v176, v177
	v_pk_mul_f32 v[176:177], v[176:177], v[176:177]
	v_add_f32_e32 v140, v140, v175
	v_add_f32_e32 v140, v140, v176
	v_add_f32_e32 v140, v140, v177
	global_store_dwordx4 v[136:137], v[182:185], off offset:-8
	s_nop 0
	v_add_f32_dpp v140, v140, v140 quad_perm:[1,0,3,2] row_mask:0xf bank_mask:0xf bound_ctrl:1
	s_nop 1
	v_add_f32_dpp v140, v140, v140 quad_perm:[2,3,0,1] row_mask:0xf bank_mask:0xf bound_ctrl:1
	s_nop 1
	v_add_f32_dpp v140, v140, v140 row_ror:4 row_mask:0xf bank_mask:0xf bound_ctrl:1
	s_nop 1
	v_mov_b32_dpp v141, v140 row_ror:8 row_mask:0xf bank_mask:0xf bound_ctrl:1
	s_and_saveexec_b64 s[16:17], s[0:1]
	s_cbranch_execz .Lop_o1b_1
	v_add_f32_e32 v140, v140, v141
	global_store_dword v[138:139], v140, off
.Lop_o1b_1:
	s_or_b64 exec, exec, s[16:17]
	s_add_u32 s14, s14, 0x20000
	s_addc_u32 s15, s15, 0
	v_lshl_add_u64 v[138:139], v[138:139], 0, s[4:5]
	v_add_u32_e32 v128, 0x8200, v128
	s_cmp_lg_u32 s14, 0x80000
	v_lshl_add_u64 v[136:137], v[136:137], 0, s[6:7]
	v_lshl_add_u64 v[180:181], v[134:135], 0, s[14:15]
	ds_read_b128 v[182:185], v128
	ds_read_b128 v[186:189], v128 offset:16
	s_waitcnt vmcnt(19) lgkmcnt(1)
	v_pk_add_f32 v[140:141], v[182:183], v[210:211]
	v_pk_add_f32 v[142:143], v[184:185], v[212:213]
	s_waitcnt vmcnt(18) lgkmcnt(0)
	v_pk_add_f32 v[174:175], v[186:187], v[226:227]
	v_pk_add_f32 v[176:177], v[188:189], v[228:229]
	global_store_dwordx4 v[180:181], v[140:143], off offset:512
	global_store_dwordx4 v[180:181], v[174:177], off offset:528
	v_cvt_pk_bf16_f32 v182, v140, v141
	v_pk_mul_f32 v[140:141], v[140:141], v[140:141]
	v_cvt_pk_bf16_f32 v183, v142, v143
	v_pk_mul_f32 v[142:143], v[142:143], v[142:143]
	v_add_f32_e32 v140, v140, v141
	v_add_f32_e32 v140, v140, v142
	v_cvt_pk_bf16_f32 v184, v174, v175
	v_pk_mul_f32 v[174:175], v[174:175], v[174:175]
	v_add_f32_e32 v140, v140, v143
	v_add_f32_e32 v140, v140, v174
	v_cvt_pk_bf16_f32 v185, v176, v177
	v_pk_mul_f32 v[176:177], v[176:177], v[176:177]
	v_add_f32_e32 v140, v140, v175
	v_add_f32_e32 v140, v140, v176
	v_add_f32_e32 v140, v140, v177
	global_store_dwordx4 v[136:137], v[182:185], off offset:-8
	s_nop 0
	v_add_f32_dpp v140, v140, v140 quad_perm:[1,0,3,2] row_mask:0xf bank_mask:0xf bound_ctrl:1
	s_nop 1
	v_add_f32_dpp v140, v140, v140 quad_perm:[2,3,0,1] row_mask:0xf bank_mask:0xf bound_ctrl:1
	s_nop 1
	v_add_f32_dpp v140, v140, v140 row_ror:4 row_mask:0xf bank_mask:0xf bound_ctrl:1
	s_nop 1
	v_mov_b32_dpp v141, v140 row_ror:8 row_mask:0xf bank_mask:0xf bound_ctrl:1
	s_and_saveexec_b64 s[16:17], s[0:1]
	s_cbranch_execz .Lop_o1b_2
	v_add_f32_e32 v140, v140, v141
	global_store_dword v[138:139], v140, off
.Lop_o1b_2:
	s_or_b64 exec, exec, s[16:17]
	s_add_u32 s14, s14, 0x20000
	s_addc_u32 s15, s15, 0
	v_lshl_add_u64 v[138:139], v[138:139], 0, s[4:5]
	v_add_u32_e32 v128, 0x8200, v128
	s_cmp_lg_u32 s14, 0x80000
	v_lshl_add_u64 v[136:137], v[136:137], 0, s[6:7]
	v_lshl_add_u64 v[180:181], v[134:135], 0, s[14:15]
	ds_read_b128 v[182:185], v128
	ds_read_b128 v[186:189], v128 offset:16
	s_waitcnt vmcnt(17) lgkmcnt(1)
	v_pk_add_f32 v[140:141], v[182:183], v[214:215]
	v_pk_add_f32 v[142:143], v[184:185], v[216:217]
	s_waitcnt vmcnt(16) lgkmcnt(0)
	v_pk_add_f32 v[174:175], v[186:187], v[230:231]
	v_pk_add_f32 v[176:177], v[188:189], v[232:233]
	global_store_dwordx4 v[180:181], v[140:143], off offset:512
	global_store_dwordx4 v[180:181], v[174:177], off offset:528
	v_cvt_pk_bf16_f32 v182, v140, v141
	v_pk_mul_f32 v[140:141], v[140:141], v[140:141]
	v_cvt_pk_bf16_f32 v183, v142, v143
	v_pk_mul_f32 v[142:143], v[142:143], v[142:143]
	v_add_f32_e32 v140, v140, v141
	v_add_f32_e32 v140, v140, v142
	v_cvt_pk_bf16_f32 v184, v174, v175
	v_pk_mul_f32 v[174:175], v[174:175], v[174:175]
	v_add_f32_e32 v140, v140, v143
	v_add_f32_e32 v140, v140, v174
	v_cvt_pk_bf16_f32 v185, v176, v177
	v_pk_mul_f32 v[176:177], v[176:177], v[176:177]
	v_add_f32_e32 v140, v140, v175
	v_add_f32_e32 v140, v140, v176
	v_add_f32_e32 v140, v140, v177
	global_store_dwordx4 v[136:137], v[182:185], off offset:-8
	s_nop 0
	v_add_f32_dpp v140, v140, v140 quad_perm:[1,0,3,2] row_mask:0xf bank_mask:0xf bound_ctrl:1
	s_nop 1
	v_add_f32_dpp v140, v140, v140 quad_perm:[2,3,0,1] row_mask:0xf bank_mask:0xf bound_ctrl:1
	s_nop 1
	v_add_f32_dpp v140, v140, v140 row_ror:4 row_mask:0xf bank_mask:0xf bound_ctrl:1
	s_nop 1
	v_mov_b32_dpp v141, v140 row_ror:8 row_mask:0xf bank_mask:0xf bound_ctrl:1
	s_and_saveexec_b64 s[16:17], s[0:1]
	s_cbranch_execz .Lop_o1b_3
	v_add_f32_e32 v140, v140, v141
	global_store_dword v[138:139], v140, off
.Lop_o1b_3:
	s_or_b64 exec, exec, s[16:17]
	s_add_u32 s14, s14, 0x20000
	s_addc_u32 s15, s15, 0
	v_lshl_add_u64 v[138:139], v[138:139], 0, s[4:5]
	v_add_u32_e32 v128, 0x8200, v128
	s_cmp_lg_u32 s14, 0x80000
	v_lshl_add_u64 v[136:137], v[136:137], 0, s[6:7]
	s_branch .LBB0_987
